# v5 (aligned) plus static s_setprio 1 for waves 4-7 inside P4 prompt-attention units (SIMD partners de-lockstepped)
# speedup vs baseline: 1.0197x; 1.0154x over previous
.LBB0_866:
	s_or_b64 exec, exec, s[8:9]
	s_setprio 0
	s_ashr_i32 s57, s56, 31
	s_lshl_b64 s[8:9], s[56:57], 11
	s_add_u32 s8, s38, s8
	s_waitcnt lgkmcnt(0)
	ds_read_b128 v[32:35], v197 offset:63488
	s_addc_u32 s9, s39, s9
	s_add_u32 s8, s8, s58
	s_addc_u32 s9, s9, 0
	v_lshlrev_b32_e32 v176, 1, v193
	v_lshl_add_u64 v[36:37], s[8:9], 0, v[176:177]
	v_lshl_add_u64 v[40:41], v[36:37], 0, s[42:43]
	ds_read_b128 v[36:39], v197 offset:63520
	s_waitcnt lgkmcnt(1)
	v_mul_f32_e32 v0, v0, v32
	v_bfe_u32 v42, v0, 16, 1
	v_lshlrev_b32_e32 v176, 13, v192
	v_add3_u32 v0, v0, v42, s66
	v_lshl_add_u64 v[42:43], v[40:41], 0, v[176:177]
	global_store_short_d16_hi v[42:43], v0, off
	v_mul_f32_e32 v0, v16, v32
	v_bfe_u32 v16, v0, 16, 1
	v_add3_u32 v0, v0, v16, s66
	global_store_short_d16_hi v[42:43], v0, off offset:64
	v_mul_f32_e32 v0, v1, v33
	v_bfe_u32 v1, v0, 16, 1
	v_add3_u32 v0, v0, v1, s66
	global_store_short_d16_hi v[42:43], v0, off offset:2048
	v_mul_f32_e32 v0, v17, v33
	v_bfe_u32 v1, v0, 16, 1
	v_add3_u32 v0, v0, v1, s66
	global_store_short_d16_hi v[42:43], v0, off offset:2112
	v_mul_f32_e32 v0, v2, v34
	v_bfe_u32 v1, v0, 16, 1
	v_add3_u32 v2, v0, v1, s66
	v_add_co_u32_e32 v0, vcc, s67, v42
	v_lshlrev_b32_e32 v176, 11, v194
	s_nop 0
	v_addc_co_u32_e32 v1, vcc, 0, v43, vcc
	global_store_short_d16_hi v[0:1], v2, off
	v_mul_f32_e32 v2, v18, v34
	v_bfe_u32 v16, v2, 16, 1
	v_add3_u32 v2, v2, v16, s66
	global_store_short_d16_hi v[0:1], v2, off offset:64
	v_mul_f32_e32 v2, v3, v35
	v_bfe_u32 v3, v2, 16, 1
	v_add3_u32 v2, v2, v3, s66
	global_store_short_d16_hi v[0:1], v2, off offset:2048
	v_mul_f32_e32 v2, v19, v35
	v_bfe_u32 v3, v2, 16, 1
	v_add3_u32 v2, v2, v3, s66
	global_store_short_d16_hi v[0:1], v2, off offset:2112
	s_waitcnt lgkmcnt(0)
	v_mul_f32_e32 v0, v4, v36
	v_bfe_u32 v1, v0, 16, 1
	v_add3_u32 v2, v0, v1, s66
	v_lshl_add_u64 v[0:1], v[40:41], 0, v[176:177]
	global_store_short_d16_hi v[0:1], v2, off
	v_mul_f32_e32 v2, v20, v36
	v_bfe_u32 v3, v2, 16, 1
	v_add3_u32 v2, v2, v3, s66
	global_store_short_d16_hi v[0:1], v2, off offset:64
	v_mul_f32_e32 v0, v5, v37
	v_bfe_u32 v1, v0, 16, 1
	v_add3_u32 v2, v0, v1, s66
	v_add_co_u32_e32 v0, vcc, s68, v42
	s_mov_b64 s[8:9], 0
	s_nop 0
	v_addc_co_u32_e32 v1, vcc, 0, v43, vcc
	global_store_short_d16_hi v[0:1], v2, off offset:2048
	v_mul_f32_e32 v2, v21, v37
	v_bfe_u32 v3, v2, 16, 1
	v_add3_u32 v2, v2, v3, s66
	global_store_short_d16_hi v[0:1], v2, off offset:2112
	v_mul_f32_e32 v0, v6, v38
	v_bfe_u32 v1, v0, 16, 1
	v_add_co_u32_e32 v4, vcc, s69, v42
	v_add3_u32 v0, v0, v1, s66
	s_nop 0
	v_addc_co_u32_e32 v5, vcc, 0, v43, vcc
	global_store_short_d16_hi v[4:5], v0, off
	v_mul_f32_e32 v0, v22, v38
	v_bfe_u32 v1, v0, 16, 1
	v_add3_u32 v0, v0, v1, s66
	global_store_short_d16_hi v[4:5], v0, off offset:64
	v_mul_f32_e32 v0, v7, v39
	v_bfe_u32 v1, v0, 16, 1
	v_add3_u32 v0, v0, v1, s66
	global_store_short_d16_hi v[4:5], v0, off offset:2048
	ds_read_b128 v[0:3], v197 offset:63552
	v_mul_f32_e32 v6, v23, v39
	v_bfe_u32 v7, v6, 16, 1
	v_add3_u32 v6, v6, v7, s66
	global_store_short_d16_hi v[4:5], v6, off offset:2112
	ds_read_b128 v[4:7], v197 offset:63584
	s_waitcnt lgkmcnt(1)
	v_mul_f32_e32 v8, v8, v0
	v_bfe_u32 v16, v8, 16, 1
	v_add3_u32 v8, v8, v16, s66
	v_add_co_u32_e32 v16, vcc, s70, v42
	v_mul_f32_e32 v0, v24, v0
	s_nop 0
	v_addc_co_u32_e32 v17, vcc, 0, v43, vcc
	v_add_co_u32_e32 v18, vcc, s71, v42
	s_nop 1
	v_addc_co_u32_e32 v19, vcc, 0, v43, vcc
	global_store_short_d16_hi v[18:19], v8, off offset:-4096
	v_bfe_u32 v8, v0, 16, 1
	v_add3_u32 v0, v0, v8, s66
	global_store_short_d16_hi v[16:17], v0, off offset:64
	v_mul_f32_e32 v0, v9, v1
	v_bfe_u32 v8, v0, 16, 1
	v_add3_u32 v0, v0, v8, s66
	global_store_short_d16_hi v[16:17], v0, off offset:2048
	v_mul_f32_e32 v0, v25, v1
	v_bfe_u32 v1, v0, 16, 1
	v_add3_u32 v0, v0, v1, s66
	global_store_short_d16_hi v[16:17], v0, off offset:2112
	v_mul_f32_e32 v0, v10, v2
	v_bfe_u32 v1, v0, 16, 1
	v_add3_u32 v0, v0, v1, s66
	global_store_short_d16_hi v[18:19], v0, off
	v_mul_f32_e32 v0, v26, v2
	v_bfe_u32 v1, v0, 16, 1
	v_add3_u32 v0, v0, v1, s66
	global_store_short_d16_hi v[18:19], v0, off offset:64
	v_mul_f32_e32 v0, v11, v3
	v_bfe_u32 v1, v0, 16, 1
	v_add3_u32 v0, v0, v1, s66
	global_store_short_d16_hi v[18:19], v0, off offset:2048
	v_mul_f32_e32 v0, v27, v3
	v_bfe_u32 v1, v0, 16, 1
	v_add3_u32 v0, v0, v1, s66
	global_store_short_d16_hi v[18:19], v0, off offset:2112
	s_waitcnt lgkmcnt(0)
	v_mul_f32_e32 v0, v12, v4
	v_bfe_u32 v1, v0, 16, 1
	v_add3_u32 v8, v0, v1, s66
	v_add_co_u32_e32 v0, vcc, s72, v42
	v_mul_f32_e32 v4, v28, v4
	s_nop 0
	v_addc_co_u32_e32 v1, vcc, 0, v43, vcc
	v_add_co_u32_e32 v2, vcc, s73, v42
	s_nop 1
	v_addc_co_u32_e32 v3, vcc, 0, v43, vcc
	global_store_short_d16_hi v[2:3], v8, off offset:-4096
	v_bfe_u32 v8, v4, 16, 1
	v_add3_u32 v4, v4, v8, s66
	global_store_short_d16_hi v[0:1], v4, off offset:64
	v_mul_f32_e32 v4, v13, v5
	v_bfe_u32 v8, v4, 16, 1
	v_add3_u32 v4, v4, v8, s66
	global_store_short_d16_hi v[0:1], v4, off offset:2048
	v_mul_f32_e32 v4, v29, v5
	v_bfe_u32 v5, v4, 16, 1
	v_add3_u32 v4, v4, v5, s66
	global_store_short_d16_hi v[0:1], v4, off offset:2112
	v_mul_f32_e32 v0, v14, v6
	v_bfe_u32 v1, v0, 16, 1
	v_add3_u32 v0, v0, v1, s66
	global_store_short_d16_hi v[2:3], v0, off
	v_mul_f32_e32 v0, v30, v6
	v_bfe_u32 v1, v0, 16, 1
	v_add3_u32 v0, v0, v1, s66
	global_store_short_d16_hi v[2:3], v0, off offset:64
	v_mul_f32_e32 v0, v15, v7
	v_bfe_u32 v1, v0, 16, 1
	v_add3_u32 v0, v0, v1, s66
	global_store_short_d16_hi v[2:3], v0, off offset:2048
	v_mul_f32_e32 v0, v31, v7
	v_bfe_u32 v1, v0, 16, 1
	v_add3_u32 v0, v0, v1, s66
	global_store_short_d16_hi v[2:3], v0, off offset:2112
	s_barrier

.LBB0_878:
	v_readfirstlane_b32 s99, v186
	s_cmpk_lt_u32 s99, 0x100
	s_cbranch_scc1 .Lmy_pa_noprio
	s_setprio 1

.LBB0_1076:
	s_ashr_i32 s29, s28, 31
	s_lshl_b64 s[30:31], s[28:29], 19
	s_add_u32 s30, s3, s30
	s_addc_u32 s31, s45, s31
	s_and_b64 s[40:41], s[6:7], exec
	s_cselect_b32 s29, s31, s53
	s_cselect_b32 s65, s30, s52
	s_ashr_i32 s27, s26, 31
	s_lshl_b64 s[40:41], s[26:27], 19
	s_add_u32 s40, s62, s40
	s_addc_u32 s41, s63, s41
	s_and_b64 s[46:47], s[6:7], exec
	s_cselect_b32 s27, s41, s55
	s_cselect_b32 s66, s40, s54
	s_add_u32 s52, s52, 0x40080
	s_addc_u32 s53, s53, 0
	s_add_u32 s67, s54, 0x100
	v_mov_b32_e32 v0, 0
	s_addc_u32 s68, s55, 0
	s_mov_b32 s69, -2
	v_mov_b32_e32 v1, v0
	v_mov_b32_e32 v2, v0
	v_mov_b32_e32 v3, v0
	v_mov_b32_e32 v4, v0
	v_mov_b32_e32 v5, v0
	v_mov_b32_e32 v6, v0
	v_mov_b32_e32 v7, v0
	v_mov_b32_e32 v16, v0
	v_mov_b32_e32 v17, v0
	v_mov_b32_e32 v18, v0
	v_mov_b32_e32 v19, v0
	v_mov_b32_e32 v20, v0
	v_mov_b32_e32 v21, v0
	v_mov_b32_e32 v22, v0
	v_mov_b32_e32 v23, v0
	v_mov_b32_e32 v32, v0
	v_mov_b32_e32 v33, v0
	v_mov_b32_e32 v34, v0
	v_mov_b32_e32 v35, v0
	v_mov_b32_e32 v36, v0
	v_mov_b32_e32 v37, v0
	v_mov_b32_e32 v38, v0
	v_mov_b32_e32 v39, v0
	v_mov_b32_e32 v48, v0
	v_mov_b32_e32 v49, v0
	v_mov_b32_e32 v50, v0
	v_mov_b32_e32 v51, v0
	v_mov_b32_e32 v52, v0
	v_mov_b32_e32 v53, v0
	v_mov_b32_e32 v54, v0
	v_mov_b32_e32 v55, v0
	v_mov_b32_e32 v8, v0
	v_mov_b32_e32 v9, v0
	v_mov_b32_e32 v10, v0
	v_mov_b32_e32 v11, v0
	v_mov_b32_e32 v12, v0
	v_mov_b32_e32 v13, v0
	v_mov_b32_e32 v14, v0
	v_mov_b32_e32 v15, v0
	v_mov_b32_e32 v24, v0
	v_mov_b32_e32 v25, v0
	v_mov_b32_e32 v26, v0
	v_mov_b32_e32 v27, v0
	v_mov_b32_e32 v28, v0
	v_mov_b32_e32 v29, v0
	v_mov_b32_e32 v30, v0
	v_mov_b32_e32 v31, v0
	v_mov_b32_e32 v40, v0
	v_mov_b32_e32 v41, v0
	v_mov_b32_e32 v42, v0
	v_mov_b32_e32 v43, v0
	v_mov_b32_e32 v44, v0
	v_mov_b32_e32 v45, v0
	v_mov_b32_e32 v46, v0
	v_mov_b32_e32 v47, v0
	v_mov_b32_e32 v56, v0
	v_mov_b32_e32 v57, v0
	v_mov_b32_e32 v58, v0
	v_mov_b32_e32 v59, v0
	v_mov_b32_e32 v60, v0
	v_mov_b32_e32 v61, v0
	v_mov_b32_e32 v62, v0
	v_mov_b32_e32 v63, v0
	v_mov_b32_e32 v64, v0
	v_mov_b32_e32 v65, v0
	v_mov_b32_e32 v66, v0
	v_mov_b32_e32 v67, v0
	v_mov_b32_e32 v68, v0
	v_mov_b32_e32 v69, v0
	v_mov_b32_e32 v70, v0
	v_mov_b32_e32 v71, v0
	v_mov_b32_e32 v80, v0
	v_mov_b32_e32 v81, v0
	v_mov_b32_e32 v82, v0
	v_mov_b32_e32 v83, v0
	v_mov_b32_e32 v84, v0
	v_mov_b32_e32 v85, v0
	v_mov_b32_e32 v86, v0
	v_mov_b32_e32 v87, v0
	v_mov_b32_e32 v96, v0
	v_mov_b32_e32 v97, v0
	v_mov_b32_e32 v98, v0
	v_mov_b32_e32 v99, v0
	v_mov_b32_e32 v100, v0
	v_mov_b32_e32 v101, v0
	v_mov_b32_e32 v102, v0
	v_mov_b32_e32 v103, v0
	v_mov_b32_e32 v112, v0
	v_mov_b32_e32 v113, v0
	v_mov_b32_e32 v114, v0
	v_mov_b32_e32 v115, v0
	v_mov_b32_e32 v116, v0
	v_mov_b32_e32 v117, v0
	v_mov_b32_e32 v118, v0
	v_mov_b32_e32 v119, v0
	v_mov_b32_e32 v72, v0
	v_mov_b32_e32 v73, v0
	v_mov_b32_e32 v74, v0
	v_mov_b32_e32 v75, v0
	v_mov_b32_e32 v76, v0
	v_mov_b32_e32 v77, v0
	v_mov_b32_e32 v78, v0
	v_mov_b32_e32 v79, v0
	v_mov_b32_e32 v88, v0
	v_mov_b32_e32 v89, v0
	v_mov_b32_e32 v90, v0
	v_mov_b32_e32 v91, v0
	v_mov_b32_e32 v92, v0
	v_mov_b32_e32 v93, v0
	v_mov_b32_e32 v94, v0
	v_mov_b32_e32 v95, v0
	v_mov_b32_e32 v104, v0
	v_mov_b32_e32 v105, v0
	v_mov_b32_e32 v106, v0
	v_mov_b32_e32 v107, v0
	v_mov_b32_e32 v108, v0
	v_mov_b32_e32 v109, v0
	v_mov_b32_e32 v110, v0
	v_mov_b32_e32 v111, v0
	v_mov_b32_e32 v120, v0
	v_mov_b32_e32 v121, v0
	v_mov_b32_e32 v122, v0
	v_mov_b32_e32 v123, v0
	v_mov_b32_e32 v124, v0
	v_mov_b32_e32 v125, v0
	v_mov_b32_e32 v126, v0
	v_mov_b32_e32 v127, v0
	s_nop 0
	s_nop 0
	s_nop 0
	s_nop 0
	s_nop 0
	s_nop 0
	s_nop 0
	s_nop 0
	s_nop 0
.LBB0_1077:
	ds_read_b128 v[144:147], v154
	ds_read_b128 v[158:161], v154 offset:1024
	ds_read_b128 v[162:165], v154 offset:2048
	ds_read_b128 v[166:169], v154 offset:3072
	ds_read_b128 v[170:173], v155
	ds_read_b128 v[174:177], v155 offset:1024
	ds_read_b128 v[178:181], v155 offset:2048
	ds_read_b128 v[182:185], v155 offset:3072
	s_add_u32 s46, s52, 0xfffc0080
	s_addc_u32 s47, s53, -1
	s_cmp_eq_u32 s69, 12
	s_cselect_b32 s57, s29, s47
	s_cselect_b32 s56, s65, s46
	s_cselect_b32 s55, s27, s68
	s_cselect_b32 s54, s66, s67
	v_lshl_add_u64 v[148:149], s[52:53], 0, v[136:137]
	s_add_i32 m0, s43, 0xc000
	ds_read_b128 v[186:189], v156
	ds_read_b128 v[190:193], v156 offset:1024
	ds_read_b128 v[198:201], v156 offset:2048
	ds_read_b128 v[202:205], v156 offset:3072
	ds_read_b128 v[206:209], v156 offset:4096
	ds_read_b128 v[210:213], v156 offset:5120
	ds_read_b128 v[214:217], v156 offset:6144
	ds_read_b128 v[218:221], v156 offset:7168
	global_load_lds_dwordx4 v[148:149], off
	v_lshl_add_u64 v[148:149], s[52:53], 0, v[138:139]
	s_add_i32 m0, s43, 0xe000
	s_nop 0
	global_load_lds_dwordx4 v[148:149], off
	s_waitcnt vmcnt(8)
	s_waitcnt lgkmcnt(0)
	s_barrier
	s_setprio 1
	s_waitcnt lgkmcnt(0)
	v_mfma_f32_16x16x32_bf16 v[124:127], v[144:147], v[186:189], v[124:127]
	v_mfma_f32_16x16x32_bf16 v[120:123], v[162:165], v[186:189], v[120:123]
	v_mfma_f32_16x16x32_bf16 v[108:111], v[144:147], v[198:201], v[108:111]
	v_mfma_f32_16x16x32_bf16 v[104:107], v[162:165], v[198:201], v[104:107]
	v_mfma_f32_16x16x32_bf16 v[92:95], v[144:147], v[206:209], v[92:95]
	v_mfma_f32_16x16x32_bf16 v[88:91], v[162:165], v[206:209], v[88:91]
	v_mfma_f32_16x16x32_bf16 v[76:79], v[144:147], v[214:217], v[76:79]
	v_mfma_f32_16x16x32_bf16 v[72:75], v[162:165], v[214:217], v[72:75]
	v_mfma_f32_16x16x32_bf16 v[124:127], v[158:161], v[190:193], v[124:127]
	v_mfma_f32_16x16x32_bf16 v[120:123], v[166:169], v[190:193], v[120:123]
	v_mfma_f32_16x16x32_bf16 v[108:111], v[158:161], v[202:205], v[108:111]
	v_mfma_f32_16x16x32_bf16 v[104:107], v[166:169], v[202:205], v[104:107]
	v_mfma_f32_16x16x32_bf16 v[92:95], v[158:161], v[210:213], v[92:95]
	v_mfma_f32_16x16x32_bf16 v[88:91], v[166:169], v[210:213], v[88:91]
	v_mfma_f32_16x16x32_bf16 v[76:79], v[158:161], v[218:221], v[76:79]
	v_mfma_f32_16x16x32_bf16 v[72:75], v[166:169], v[218:221], v[72:75]
	s_setprio 0
	s_setprio 1
	v_mfma_f32_16x16x32_bf16 v[116:119], v[170:173], v[186:189], v[116:119]
	v_mfma_f32_16x16x32_bf16 v[112:115], v[178:181], v[186:189], v[112:115]
	v_mfma_f32_16x16x32_bf16 v[100:103], v[170:173], v[198:201], v[100:103]
	v_mfma_f32_16x16x32_bf16 v[96:99], v[178:181], v[198:201], v[96:99]
	v_mfma_f32_16x16x32_bf16 v[84:87], v[170:173], v[206:209], v[84:87]
	v_mfma_f32_16x16x32_bf16 v[80:83], v[178:181], v[206:209], v[80:83]
	v_mfma_f32_16x16x32_bf16 v[68:71], v[170:173], v[214:217], v[68:71]
	v_mfma_f32_16x16x32_bf16 v[64:67], v[178:181], v[214:217], v[64:67]
	v_mfma_f32_16x16x32_bf16 v[116:119], v[174:177], v[190:193], v[116:119]
	v_mfma_f32_16x16x32_bf16 v[112:115], v[182:185], v[190:193], v[112:115]
	v_mfma_f32_16x16x32_bf16 v[100:103], v[174:177], v[202:205], v[100:103]
	v_mfma_f32_16x16x32_bf16 v[96:99], v[182:185], v[202:205], v[96:99]
	v_mfma_f32_16x16x32_bf16 v[84:87], v[174:177], v[210:213], v[84:87]
	v_mfma_f32_16x16x32_bf16 v[80:83], v[182:185], v[210:213], v[80:83]
	v_mfma_f32_16x16x32_bf16 v[68:71], v[174:177], v[218:221], v[68:71]
	v_mfma_f32_16x16x32_bf16 v[64:67], v[182:185], v[218:221], v[64:67]
	s_setprio 0
	s_barrier
	s_add_i32 s46, s61, s4
	v_lshl_add_u64 v[148:149], s[54:55], 0, v[132:133]
	s_mov_b32 m0, s46
	ds_read_b128 v[186:189], v156 offset:16384
	ds_read_b128 v[190:193], v156 offset:17408
	ds_read_b128 v[198:201], v156 offset:18432
	ds_read_b128 v[202:205], v156 offset:19456
	ds_read_b128 v[206:209], v156 offset:20480
	ds_read_b128 v[210:213], v156 offset:21504
	ds_read_b128 v[214:217], v156 offset:22528
	ds_read_b128 v[218:221], v156 offset:23552
	global_load_lds_dwordx4 v[148:149], off
	s_add_i32 m0, s46, 0x2000
	s_add_u32 s46, s54, 0x40000
	v_lshl_add_u64 v[194:195], s[54:55], 0, v[128:129]
	s_addc_u32 s47, s55, 0
	s_add_i32 s70, s64, s4
	global_load_lds_dwordx4 v[194:195], off
	v_lshl_add_u64 v[196:197], s[46:47], 0, v[132:133]
	s_mov_b32 m0, s70
	v_lshl_add_u64 v[222:223], s[56:57], 0, v[130:131]
	global_load_lds_dwordx4 v[196:197], off
	v_lshl_add_u64 v[196:197], s[46:47], 0, v[128:129]
	s_add_i32 m0, s70, 0x2000
	s_nop 0
	global_load_lds_dwordx4 v[196:197], off
	v_lshl_add_u64 v[196:197], s[56:57], 0, v[134:135]
	s_mov_b32 m0, s43
	s_nop 0
	global_load_lds_dwordx4 v[196:197], off
	s_mov_b32 m0, s48
	s_nop 0
	global_load_lds_dwordx4 v[222:223], off
	s_nop 0
	s_waitcnt vmcnt(8)
	s_waitcnt lgkmcnt(0)
	s_barrier
	s_setprio 1
	s_waitcnt lgkmcnt(0)
	v_mfma_f32_16x16x32_bf16 v[60:63], v[144:147], v[186:189], v[60:63]
	v_mfma_f32_16x16x32_bf16 v[56:59], v[162:165], v[186:189], v[56:59]
	v_mfma_f32_16x16x32_bf16 v[44:47], v[144:147], v[198:201], v[44:47]
	v_mfma_f32_16x16x32_bf16 v[40:43], v[162:165], v[198:201], v[40:43]
	v_mfma_f32_16x16x32_bf16 v[28:31], v[144:147], v[206:209], v[28:31]
	v_mfma_f32_16x16x32_bf16 v[24:27], v[162:165], v[206:209], v[24:27]
	v_mfma_f32_16x16x32_bf16 v[12:15], v[144:147], v[214:217], v[12:15]
	v_mfma_f32_16x16x32_bf16 v[8:11], v[162:165], v[214:217], v[8:11]
	v_mfma_f32_16x16x32_bf16 v[60:63], v[158:161], v[190:193], v[60:63]
	v_mfma_f32_16x16x32_bf16 v[56:59], v[166:169], v[190:193], v[56:59]
	v_mfma_f32_16x16x32_bf16 v[44:47], v[158:161], v[202:205], v[44:47]
	v_mfma_f32_16x16x32_bf16 v[40:43], v[166:169], v[202:205], v[40:43]
	v_mfma_f32_16x16x32_bf16 v[28:31], v[158:161], v[210:213], v[28:31]
	v_mfma_f32_16x16x32_bf16 v[24:27], v[166:169], v[210:213], v[24:27]
	v_mfma_f32_16x16x32_bf16 v[12:15], v[158:161], v[218:221], v[12:15]
	v_mfma_f32_16x16x32_bf16 v[8:11], v[166:169], v[218:221], v[8:11]
	s_setprio 0
	s_setprio 1
	v_mfma_f32_16x16x32_bf16 v[52:55], v[170:173], v[186:189], v[52:55]
	v_mfma_f32_16x16x32_bf16 v[48:51], v[178:181], v[186:189], v[48:51]
	v_mfma_f32_16x16x32_bf16 v[36:39], v[170:173], v[198:201], v[36:39]
	v_mfma_f32_16x16x32_bf16 v[32:35], v[178:181], v[198:201], v[32:35]
	v_mfma_f32_16x16x32_bf16 v[20:23], v[170:173], v[206:209], v[20:23]
	v_mfma_f32_16x16x32_bf16 v[16:19], v[178:181], v[206:209], v[16:19]
	v_mfma_f32_16x16x32_bf16 v[4:7], v[170:173], v[214:217], v[4:7]
	v_mfma_f32_16x16x32_bf16 v[0:3], v[178:181], v[214:217], v[0:3]
	v_mfma_f32_16x16x32_bf16 v[52:55], v[174:177], v[190:193], v[52:55]
	v_mfma_f32_16x16x32_bf16 v[48:51], v[182:185], v[190:193], v[48:51]
	v_mfma_f32_16x16x32_bf16 v[36:39], v[174:177], v[202:205], v[36:39]
	v_mfma_f32_16x16x32_bf16 v[32:35], v[182:185], v[202:205], v[32:35]
	v_mfma_f32_16x16x32_bf16 v[20:23], v[174:177], v[210:213], v[20:23]
	v_mfma_f32_16x16x32_bf16 v[16:19], v[182:185], v[210:213], v[16:19]
	v_mfma_f32_16x16x32_bf16 v[4:7], v[174:177], v[218:221], v[4:7]
	v_mfma_f32_16x16x32_bf16 v[0:3], v[182:185], v[218:221], v[0:3]
	s_setprio 0
	s_barrier
	s_add_i32 s70, 0, 0x18000
	v_add_u32_e32 v157, s70, v152
	s_add_i32 s71, 0, 0x1c000
	ds_read_b128 v[144:147], v157
	ds_read_b128 v[158:161], v157 offset:1024
	ds_read_b128 v[162:165], v157 offset:2048
	ds_read_b128 v[166:169], v157 offset:3072
	v_add_u32_e32 v157, s71, v152
	ds_read_b128 v[170:173], v157
	ds_read_b128 v[174:177], v157 offset:1024
	ds_read_b128 v[178:181], v157 offset:2048
	ds_read_b128 v[182:185], v157 offset:3072
	s_add_u32 s46, s56, 0x40000
	s_addc_u32 s47, s57, 0
	s_mov_b32 m0, s49
	v_lshl_add_u64 v[224:225], s[46:47], 0, v[134:135]
	ds_read_b128 v[186:189], v156 offset:32768
	ds_read_b128 v[190:193], v156 offset:33792
	ds_read_b128 v[198:201], v156 offset:34816
	ds_read_b128 v[202:205], v156 offset:35840
	ds_read_b128 v[206:209], v156 offset:36864
	ds_read_b128 v[210:213], v156 offset:37888
	ds_read_b128 v[214:217], v156 offset:38912
	ds_read_b128 v[218:221], v156 offset:39936
	global_load_lds_dwordx4 v[224:225], off
	v_lshl_add_u64 v[224:225], s[46:47], 0, v[130:131]
	s_mov_b32 m0, s50
	s_nop 0
	global_load_lds_dwordx4 v[224:225], off
	s_nop 0
	s_waitcnt vmcnt(8)
	s_waitcnt lgkmcnt(0)
	s_barrier
	s_setprio 1
	s_waitcnt lgkmcnt(0)
	v_mfma_f32_16x16x32_bf16 v[124:127], v[144:147], v[186:189], v[124:127]
	v_mfma_f32_16x16x32_bf16 v[120:123], v[162:165], v[186:189], v[120:123]
	v_mfma_f32_16x16x32_bf16 v[108:111], v[144:147], v[198:201], v[108:111]
	v_mfma_f32_16x16x32_bf16 v[104:107], v[162:165], v[198:201], v[104:107]
	v_mfma_f32_16x16x32_bf16 v[92:95], v[144:147], v[206:209], v[92:95]
	v_mfma_f32_16x16x32_bf16 v[88:91], v[162:165], v[206:209], v[88:91]
	v_mfma_f32_16x16x32_bf16 v[76:79], v[144:147], v[214:217], v[76:79]
	v_mfma_f32_16x16x32_bf16 v[72:75], v[162:165], v[214:217], v[72:75]
	v_mfma_f32_16x16x32_bf16 v[124:127], v[158:161], v[190:193], v[124:127]
	v_mfma_f32_16x16x32_bf16 v[120:123], v[166:169], v[190:193], v[120:123]
	v_mfma_f32_16x16x32_bf16 v[108:111], v[158:161], v[202:205], v[108:111]
	v_mfma_f32_16x16x32_bf16 v[104:107], v[166:169], v[202:205], v[104:107]
	v_mfma_f32_16x16x32_bf16 v[92:95], v[158:161], v[210:213], v[92:95]
	v_mfma_f32_16x16x32_bf16 v[88:91], v[166:169], v[210:213], v[88:91]
	v_mfma_f32_16x16x32_bf16 v[76:79], v[158:161], v[218:221], v[76:79]
	v_mfma_f32_16x16x32_bf16 v[72:75], v[166:169], v[218:221], v[72:75]
	s_setprio 0
	s_setprio 1
	v_mfma_f32_16x16x32_bf16 v[116:119], v[170:173], v[186:189], v[116:119]
	v_mfma_f32_16x16x32_bf16 v[112:115], v[178:181], v[186:189], v[112:115]
	v_mfma_f32_16x16x32_bf16 v[100:103], v[170:173], v[198:201], v[100:103]
	v_mfma_f32_16x16x32_bf16 v[96:99], v[178:181], v[198:201], v[96:99]
	v_mfma_f32_16x16x32_bf16 v[84:87], v[170:173], v[206:209], v[84:87]
	v_mfma_f32_16x16x32_bf16 v[80:83], v[178:181], v[206:209], v[80:83]
	v_mfma_f32_16x16x32_bf16 v[68:71], v[170:173], v[214:217], v[68:71]
	v_mfma_f32_16x16x32_bf16 v[64:67], v[178:181], v[214:217], v[64:67]
	v_mfma_f32_16x16x32_bf16 v[116:119], v[174:177], v[190:193], v[116:119]
	v_mfma_f32_16x16x32_bf16 v[112:115], v[182:185], v[190:193], v[112:115]
	v_mfma_f32_16x16x32_bf16 v[100:103], v[174:177], v[202:205], v[100:103]
	v_mfma_f32_16x16x32_bf16 v[96:99], v[182:185], v[202:205], v[96:99]
	v_mfma_f32_16x16x32_bf16 v[84:87], v[174:177], v[210:213], v[84:87]
	v_mfma_f32_16x16x32_bf16 v[80:83], v[182:185], v[210:213], v[80:83]
	v_mfma_f32_16x16x32_bf16 v[68:71], v[174:177], v[218:221], v[68:71]
	v_mfma_f32_16x16x32_bf16 v[64:67], v[182:185], v[218:221], v[64:67]
	s_setprio 0
	s_barrier
	s_add_i32 s46, s70, s4
	v_lshl_add_u64 v[148:149], v[148:149], 0, s[16:17]
	s_mov_b32 m0, s46
	ds_read_b128 v[186:189], v156 offset:49152
	ds_read_b128 v[190:193], v156 offset:50176
	ds_read_b128 v[198:201], v156 offset:51200
	ds_read_b128 v[202:205], v156 offset:52224
	ds_read_b128 v[206:209], v156 offset:53248
	ds_read_b128 v[210:213], v156 offset:54272
	ds_read_b128 v[214:217], v156 offset:55296
	ds_read_b128 v[218:221], v156 offset:56320
	global_load_lds_dwordx4 v[148:149], off
	s_add_i32 m0, s46, 0x2000
	s_add_u32 s46, s54, 0x40080
	v_lshl_add_u64 v[148:149], v[194:195], 0, s[16:17]
	s_addc_u32 s47, s55, 0
	s_add_i32 s54, s71, s4
	global_load_lds_dwordx4 v[148:149], off
	v_lshl_add_u64 v[148:149], s[46:47], 0, v[132:133]
	s_mov_b32 m0, s54
	s_nop 0
	global_load_lds_dwordx4 v[148:149], off
	v_lshl_add_u64 v[148:149], s[46:47], 0, v[128:129]
	s_add_i32 m0, s54, 0x2000
	s_nop 0
	global_load_lds_dwordx4 v[148:149], off
	v_lshl_add_u64 v[148:149], v[196:197], 0, s[16:17]
	s_mov_b32 m0, s58
	s_nop 0
	global_load_lds_dwordx4 v[148:149], off
	v_lshl_add_u64 v[148:149], v[222:223], 0, s[16:17]
	s_mov_b32 m0, s59
	s_nop 0
	global_load_lds_dwordx4 v[148:149], off
	s_waitcnt vmcnt(8)
	s_waitcnt lgkmcnt(0)
	s_barrier
	s_setprio 1
	s_waitcnt lgkmcnt(0)
	v_mfma_f32_16x16x32_bf16 v[60:63], v[144:147], v[186:189], v[60:63]
	v_mfma_f32_16x16x32_bf16 v[56:59], v[162:165], v[186:189], v[56:59]
	v_mfma_f32_16x16x32_bf16 v[44:47], v[144:147], v[198:201], v[44:47]
	v_mfma_f32_16x16x32_bf16 v[40:43], v[162:165], v[198:201], v[40:43]
	v_mfma_f32_16x16x32_bf16 v[28:31], v[144:147], v[206:209], v[28:31]
	v_mfma_f32_16x16x32_bf16 v[24:27], v[162:165], v[206:209], v[24:27]
	v_mfma_f32_16x16x32_bf16 v[12:15], v[144:147], v[214:217], v[12:15]
	v_mfma_f32_16x16x32_bf16 v[8:11], v[162:165], v[214:217], v[8:11]
	v_mfma_f32_16x16x32_bf16 v[60:63], v[158:161], v[190:193], v[60:63]
	v_mfma_f32_16x16x32_bf16 v[56:59], v[166:169], v[190:193], v[56:59]
	v_mfma_f32_16x16x32_bf16 v[44:47], v[158:161], v[202:205], v[44:47]
	v_mfma_f32_16x16x32_bf16 v[40:43], v[166:169], v[202:205], v[40:43]
	v_mfma_f32_16x16x32_bf16 v[28:31], v[158:161], v[210:213], v[28:31]
	v_mfma_f32_16x16x32_bf16 v[24:27], v[166:169], v[210:213], v[24:27]
	v_mfma_f32_16x16x32_bf16 v[12:15], v[158:161], v[218:221], v[12:15]
	v_mfma_f32_16x16x32_bf16 v[8:11], v[166:169], v[218:221], v[8:11]
	s_setprio 0
	s_setprio 1
	v_mfma_f32_16x16x32_bf16 v[52:55], v[170:173], v[186:189], v[52:55]
	v_mfma_f32_16x16x32_bf16 v[48:51], v[178:181], v[186:189], v[48:51]
	v_mfma_f32_16x16x32_bf16 v[36:39], v[170:173], v[198:201], v[36:39]
	v_mfma_f32_16x16x32_bf16 v[32:35], v[178:181], v[198:201], v[32:35]
	v_mfma_f32_16x16x32_bf16 v[20:23], v[170:173], v[206:209], v[20:23]
	v_mfma_f32_16x16x32_bf16 v[16:19], v[178:181], v[206:209], v[16:19]
	v_mfma_f32_16x16x32_bf16 v[4:7], v[170:173], v[214:217], v[4:7]
	v_mfma_f32_16x16x32_bf16 v[0:3], v[178:181], v[214:217], v[0:3]
	v_mfma_f32_16x16x32_bf16 v[52:55], v[174:177], v[190:193], v[52:55]
	v_mfma_f32_16x16x32_bf16 v[48:51], v[182:185], v[190:193], v[48:51]
	v_mfma_f32_16x16x32_bf16 v[36:39], v[174:177], v[202:205], v[36:39]
	v_mfma_f32_16x16x32_bf16 v[32:35], v[182:185], v[202:205], v[32:35]
	v_mfma_f32_16x16x32_bf16 v[20:23], v[174:177], v[210:213], v[20:23]
	v_mfma_f32_16x16x32_bf16 v[16:19], v[182:185], v[210:213], v[16:19]
	v_mfma_f32_16x16x32_bf16 v[4:7], v[174:177], v[218:221], v[4:7]
	v_mfma_f32_16x16x32_bf16 v[0:3], v[182:185], v[218:221], v[0:3]
	s_setprio 0
	s_barrier
	s_add_i32 s69, s69, 2
	s_add_u32 s52, s52, 0x100
	s_addc_u32 s53, s53, 0
	s_add_u32 s67, s67, 0x100
	s_addc_u32 s68, s68, 0
	s_cmp_gt_u32 s69, 13
	s_cbranch_scc0 .LBB0_1077
	s_and_b64 vcc, exec, s[18:19]
	s_cbranch_vccz .LBB0_1080
	s_barrier
